# LRU tile: 19 conv-window loads issued together with one wait instead of one branch+vmcnt(0) each
# speedup vs baseline: 1.0098x; 1.0098x over previous
; #define LAS __attribute__((address_space(3)))
; __device__ __forceinline__ float bf2f(bf16 b) { return __uint_as_float((unsigned)b << 16); }
; __device__ __forceinline__ bf16 f2bf_hw(float x) { return (bf16)(pk2(x, x) & 0xffffu); }
; __device__ __forceinline__ void lru_unit(const Ctx& C, const Params& p, int l, int unit) {
;     ...
;         const int tl0 = tile * 128 + 16 * tg, t0 = tc * 256 + tl0;
;         float xw[19], gbv[16], xc[16];
; #pragma unroll
;         for (int k = 0; k < 19; ++k) { const int t = t0 - 3 + k; xw[k] = (t >= 0) ? bf2f(Zb[(size_t)t * ZC + XB + ch]) : 0.f; }
; #pragma unroll
;         for (int i = 0; i < 16; ++i) gbv[i] = bf2f(Zb[(size_t)(t0 + i) * ZC + GB + ch]);
; #pragma unroll
;         for (int i = 0; i < 16; ++i) { xc[i] = cb + cw0 * xw[i] + cw1 * xw[i + 1] + cw2 * xw[i + 2] + cw3 * xw[i + 3];
;             *(LAS bf16*)(XCB + (16 * tg + i) * 144 + c * 2) = f2bf_hw(xc[i]); }
.LBB0_327:
	v_add_u32_e32 v71, s24, v125
	v_add_u32_e32 v73, s21, v71
	v_lshlrev_b32_e32 v192, 1, v114
	v_mov_b64_e32 v[112:113], s[50:51]
	v_lshl_add_u64 v[112:113], v[112:113], 0, v[192:193]
	v_add_co_u32_e32 v112, vcc, 0x1000, v112
	v_add_u32_e32 v65, -3, v73
	v_add_u32_e32 v64, -2, v73
	v_addc_co_u32_e32 v113, vcc, 0, v113, vcc
	v_add_u32_e32 v67, -1, v73
	v_max_i32_e32 v65, 0, v65
	v_max_i32_e32 v64, 0, v64
	v_max_i32_e32 v67, 0, v67
	v_or_b32_e32 v74, 1, v73
	v_or_b32_e32 v79, 2, v73
	v_or_b32_e32 v80, 3, v73
	v_or_b32_e32 v81, 4, v73
	v_or_b32_e32 v84, 5, v73
	v_or_b32_e32 v86, 6, v73
	v_or_b32_e32 v92, 7, v73
	v_or_b32_e32 v87, 8, v73
	v_or_b32_e32 v93, 9, v73
	v_or_b32_e32 v98, 10, v73
	v_or_b32_e32 v99, 11, v73
	v_or_b32_e32 v104, 12, v73
	v_or_b32_e32 v105, 13, v73
	v_or_b32_e32 v108, 14, v73
	v_or_b32_e32 v110, 15, v73
	v_mad_u64_u32 v[150:151], s[22:23], v65, s33, v[112:113]
	global_load_ushort v65, v[150:151], off offset:512
	v_mad_u64_u32 v[152:153], s[22:23], v64, s33, v[112:113]
	global_load_ushort v64, v[152:153], off offset:512
	v_mad_u64_u32 v[150:151], s[22:23], v67, s33, v[112:113]
	global_load_ushort v67, v[150:151], off offset:512
	v_mad_u64_u32 v[152:153], s[22:23], v73, s33, v[112:113]
	global_load_ushort v66, v[152:153], off offset:512
	v_mad_u64_u32 v[150:151], s[22:23], v74, s33, v[112:113]
	global_load_ushort v69, v[150:151], off offset:512
	v_mad_u64_u32 v[152:153], s[22:23], v79, s33, v[112:113]
	global_load_ushort v68, v[152:153], off offset:512
	v_mad_u64_u32 v[150:151], s[22:23], v80, s33, v[112:113]
	global_load_ushort v72, v[150:151], off offset:512
	v_mad_u64_u32 v[152:153], s[22:23], v81, s33, v[112:113]
	global_load_ushort v70, v[152:153], off offset:512
	v_mad_u64_u32 v[150:151], s[22:23], v84, s33, v[112:113]
	global_load_ushort v76, v[150:151], off offset:512
	v_mad_u64_u32 v[152:153], s[22:23], v86, s33, v[112:113]
	global_load_ushort v75, v[152:153], off offset:512
	v_mad_u64_u32 v[150:151], s[22:23], v92, s33, v[112:113]
	global_load_ushort v82, v[150:151], off offset:512
	v_mad_u64_u32 v[152:153], s[22:23], v87, s33, v[112:113]
	global_load_ushort v78, v[152:153], off offset:512
	v_mad_u64_u32 v[150:151], s[22:23], v93, s33, v[112:113]
	global_load_ushort v90, v[150:151], off offset:512
	v_mad_u64_u32 v[152:153], s[22:23], v98, s33, v[112:113]
	global_load_ushort v88, v[152:153], off offset:512
	v_mad_u64_u32 v[150:151], s[22:23], v99, s33, v[112:113]
	global_load_ushort v96, v[150:151], off offset:512
	v_mad_u64_u32 v[152:153], s[22:23], v104, s33, v[112:113]
	global_load_ushort v94, v[152:153], off offset:512
	v_mad_u64_u32 v[150:151], s[22:23], v105, s33, v[112:113]
	global_load_ushort v102, v[150:151], off offset:512
	v_mad_u64_u32 v[152:153], s[22:23], v108, s33, v[112:113]
	global_load_ushort v100, v[152:153], off offset:512
	v_mad_u64_u32 v[150:151], s[22:23], v110, s33, v[112:113]
	global_load_ushort v106, v[150:151], off offset:512
	s_waitcnt vmcnt(0)
	v_cmp_ne_u32_e32 vcc, 0, v73
	v_lshlrev_b32_e32 v65, 16, v65
	v_lshlrev_b32_e32 v64, 16, v64
	v_lshlrev_b32_e32 v67, 16, v67
	v_cndmask_b32_e32 v65, 0, v65, vcc
	v_cndmask_b32_e32 v64, 0, v64, vcc
	v_cndmask_b32_e32 v67, 0, v67, vcc
	v_lshlrev_b32_e32 v66, 16, v66
	v_lshlrev_b32_e32 v69, 16, v69
	v_lshlrev_b32_e32 v68, 16, v68
	v_lshlrev_b32_e32 v72, 16, v72
	v_lshlrev_b32_e32 v70, 16, v70
	v_lshlrev_b32_e32 v76, 16, v76
	v_lshlrev_b32_e32 v75, 16, v75
	v_lshlrev_b32_e32 v82, 16, v82
	v_lshlrev_b32_e32 v78, 16, v78
	v_lshlrev_b32_e32 v90, 16, v90
	v_lshlrev_b32_e32 v88, 16, v88
	v_lshlrev_b32_e32 v96, 16, v96
	v_lshlrev_b32_e32 v94, 16, v94
	v_lshlrev_b32_e32 v102, 16, v102
	v_lshlrev_b32_e32 v100, 16, v100
	v_lshlrev_b32_e32 v106, 16, v106
	v_mov_b64_e32 v[112:113], s[50:51]
	v_mad_i64_i32 v[150:151], s[22:23], v73, s33, v[112:113]
	v_lshl_add_u64 v[150:151], v[150:151], 0, v[192:193]
	v_add_co_u32_e32 v150, vcc, 0x1000, v150
	s_nop 1
	v_addc_co_u32_e32 v151, vcc, 0, v151, vcc
	global_load_ushort v73, v[150:151], off offset:1536
	v_mad_i64_i32 v[150:151], s[22:23], v74, s33, v[112:113]
	v_lshl_add_u64 v[150:151], v[150:151], 0, v[192:193]
	v_add_co_u32_e32 v150, vcc, 0x1000, v150
	v_fma_f32 v74, v115, v69, v119
	s_nop 0
	v_addc_co_u32_e32 v151, vcc, 0, v151, vcc
	global_load_ushort v77, v[150:151], off offset:1536
	v_mad_i64_i32 v[150:151], s[22:23], v79, s33, v[112:113]
	v_lshl_add_u64 v[150:151], v[150:151], 0, v[192:193]
	v_add_co_u32_e32 v150, vcc, 0x1000, v150
	v_fmac_f32_e32 v74, v116, v68
	s_nop 0
	v_addc_co_u32_e32 v151, vcc, 0, v151, vcc
	global_load_ushort v79, v[150:151], off offset:1536
	v_mad_i64_i32 v[150:151], s[22:23], v80, s33, v[112:113]
	v_lshl_add_u64 v[150:151], v[150:151], 0, v[192:193]
	v_add_co_u32_e32 v150, vcc, 0x1000, v150
	v_mad_i64_i32 v[80:81], s[22:23], v81, s33, v[112:113]
	s_nop 0
	v_addc_co_u32_e32 v151, vcc, 0, v151, vcc
	v_lshl_add_u64 v[80:81], v[80:81], 0, v[192:193]
	v_add_co_u32_e32 v80, vcc, 0x1000, v80
	global_load_ushort v83, v[150:151], off offset:1536
	s_nop 0
	v_addc_co_u32_e32 v81, vcc, 0, v81, vcc
	global_load_ushort v85, v[80:81], off offset:1536
	v_mad_i64_i32 v[80:81], s[22:23], v84, s33, v[112:113]
	v_lshl_add_u64 v[80:81], v[80:81], 0, v[192:193]
	v_add_co_u32_e32 v80, vcc, 0x1000, v80
	v_fma_f32 v84, v115, v66, v119
	s_nop 0
	v_addc_co_u32_e32 v81, vcc, 0, v81, vcc
	global_load_ushort v89, v[80:81], off offset:1536
	v_mad_i64_i32 v[80:81], s[22:23], v86, s33, v[112:113]
	v_lshl_add_u64 v[80:81], v[80:81], 0, v[192:193]
	v_add_co_u32_e32 v80, vcc, 0x1000, v80
	v_fmac_f32_e32 v84, v116, v69
	s_nop 0
	v_addc_co_u32_e32 v81, vcc, 0, v81, vcc
	global_load_ushort v91, v[80:81], off offset:1536
; #define LAS __attribute__((address_space(3)))
; __device__ __forceinline__ float bf2f(bf16 b) { return __uint_as_float((unsigned)b << 16); }
; __device__ __forceinline__ bf16 f2bf_hw(float x) { return (bf16)(pk2(x, x) & 0xffffu); }
; __device__ __forceinline__ void lru_unit(const Ctx& C, const Params& p, int l, int unit) {
;     ...
;         for (int k = 0; k < 19; ++k) { const int t = t0 - 3 + k; xw[k] = (t >= 0) ? bf2f(Zb[(size_t)t * ZC + XB + ch]) : 0.f; }
; #pragma unroll
;         for (int i = 0; i < 16; ++i) gbv[i] = bf2f(Zb[(size_t)(t0 + i) * ZC + GB + ch]);
; #pragma unroll
;         for (int i = 0; i < 16; ++i) { xc[i] = cb + cw0 * xw[i] + cw1 * xw[i + 1] + cw2 * xw[i + 2] + cw3 * xw[i + 3];
;             *(LAS bf16*)(XCB + (16 * tg + i) * 144 + c * 2) = f2bf_hw(xc[i]); }
;         __syncthreads();
	v_mad_i64_i32 v[80:81], s[22:23], v92, s33, v[112:113]
	v_lshl_add_u64 v[80:81], v[80:81], 0, v[192:193]
	v_add_co_u32_e32 v80, vcc, 0x1000, v80
	v_fmac_f32_e32 v84, v117, v68
	s_nop 0
	v_addc_co_u32_e32 v81, vcc, 0, v81, vcc
	global_load_ushort v95, v[80:81], off offset:1536
	v_mad_i64_i32 v[80:81], s[22:23], v87, s33, v[112:113]
	v_lshl_add_u64 v[80:81], v[80:81], 0, v[192:193]
	v_add_co_u32_e32 v80, vcc, 0x1000, v80
	v_fmac_f32_e32 v84, v118, v72
	s_nop 0
	v_addc_co_u32_e32 v81, vcc, 0, v81, vcc
	global_load_ushort v97, v[80:81], off offset:1536
	v_mad_i64_i32 v[80:81], s[22:23], v93, s33, v[112:113]
	v_lshl_add_u64 v[80:81], v[80:81], 0, v[192:193]
	v_add_co_u32_e32 v80, vcc, 0x1000, v80
	v_fmac_f32_e32 v74, v117, v72
	s_nop 0
	v_addc_co_u32_e32 v81, vcc, 0, v81, vcc
	global_load_ushort v101, v[80:81], off offset:1536
	v_mad_i64_i32 v[80:81], s[22:23], v98, s33, v[112:113]
	v_lshl_add_u64 v[80:81], v[80:81], 0, v[192:193]
	v_add_co_u32_e32 v80, vcc, 0x1000, v80
	v_fmac_f32_e32 v74, v118, v70
	s_nop 0
	v_addc_co_u32_e32 v81, vcc, 0, v81, vcc
	global_load_ushort v107, v[80:81], off offset:1536
	v_mad_i64_i32 v[80:81], s[22:23], v99, s33, v[112:113]
	v_lshl_add_u64 v[80:81], v[80:81], 0, v[192:193]
	v_add_co_u32_e32 v80, vcc, 0x1000, v80
	v_fma_f32 v87, v115, v70, v119
	s_nop 0
	v_addc_co_u32_e32 v81, vcc, 0, v81, vcc
	global_load_ushort v103, v[80:81], off offset:1536
	v_mad_i64_i32 v[80:81], s[22:23], v104, s33, v[112:113]
	v_lshl_add_u64 v[80:81], v[80:81], 0, v[192:193]
	v_add_co_u32_e32 v80, vcc, 0x1000, v80
	v_fmac_f32_e32 v87, v116, v76
	s_nop 0
	v_addc_co_u32_e32 v81, vcc, 0, v81, vcc
	global_load_ushort v109, v[80:81], off offset:1536
	v_mad_i64_i32 v[80:81], s[22:23], v105, s33, v[112:113]
	v_lshl_add_u64 v[80:81], v[80:81], 0, v[192:193]
	v_add_co_u32_e32 v80, vcc, 0x1000, v80
	v_fma_f32 v86, v115, v76, v119
	s_nop 0
	v_addc_co_u32_e32 v81, vcc, 0, v81, vcc
	global_load_ushort v111, v[80:81], off offset:1536
	v_mad_i64_i32 v[80:81], s[22:23], v108, s33, v[112:113]
	v_lshl_add_u64 v[80:81], v[80:81], 0, v[192:193]
	v_add_co_u32_e32 v80, vcc, 0x1000, v80
	v_fma_f32 v108, v115, v65, v119
	s_nop 0
	v_addc_co_u32_e32 v81, vcc, 0, v81, vcc
	global_load_ushort v150, v[80:81], off offset:1536
	v_mad_i64_i32 v[80:81], s[22:23], v110, s33, v[112:113]
	v_fma_f32 v110, v115, v64, v119
	v_lshl_add_u64 v[80:81], v[80:81], 0, v[192:193]
	v_fmac_f32_e32 v110, v116, v67
	v_fma_f32 v112, v115, v67, v119
	v_add_co_u32_e32 v80, vcc, 0x1000, v80
	v_fmac_f32_e32 v110, v117, v66
	v_fmac_f32_e32 v112, v116, v66
	v_addc_co_u32_e32 v81, vcc, 0, v81, vcc
	v_fmac_f32_e32 v110, v118, v69
	v_fmac_f32_e32 v112, v117, v69
	global_load_ushort v151, v[80:81], off offset:1536
	v_fmac_f32_e32 v108, v116, v64
	v_cvt_pk_bf16_f32 v64, v110, s0
	v_fmac_f32_e32 v112, v118, v68
	v_fma_f32 v81, v115, v68, v119
	ds_write_b16 v131, v64 offset:64
	v_cvt_pk_bf16_f32 v64, v112, s0
	v_fmac_f32_e32 v81, v116, v72
	v_fma_f32 v80, v115, v72, v119
	ds_write_b16 v131, v64 offset:208
	v_cvt_pk_bf16_f32 v64, v84, s0
	v_fmac_f32_e32 v81, v117, v70
	v_fmac_f32_e32 v80, v116, v70
	ds_write_b16 v131, v64 offset:352
	v_cvt_pk_bf16_f32 v64, v74, s0
	v_fmac_f32_e32 v81, v118, v76
	v_fmac_f32_e32 v80, v117, v76
	ds_write_b16 v131, v64 offset:496
	v_cvt_pk_bf16_f32 v64, v81, s0
	v_fmac_f32_e32 v80, v118, v75
	v_fmac_f32_e32 v87, v117, v75
	v_fmac_f32_e32 v86, v116, v75
	v_fma_f32 v93, v115, v75, v119
	ds_write_b16 v131, v64 offset:640
	v_cvt_pk_bf16_f32 v64, v80, s0
	v_fmac_f32_e32 v87, v118, v82
	v_fmac_f32_e32 v86, v117, v82
	v_fmac_f32_e32 v93, v116, v82
	v_fma_f32 v92, v115, v82, v119
	ds_write_b16 v131, v64 offset:784
	v_cvt_pk_bf16_f32 v64, v87, s0
	v_fmac_f32_e32 v86, v118, v78
	v_fmac_f32_e32 v93, v117, v78
	v_fmac_f32_e32 v92, v116, v78
	v_fma_f32 v99, v115, v78, v119
	ds_write_b16 v131, v64 offset:928
	v_cvt_pk_bf16_f32 v64, v86, s0
	v_fmac_f32_e32 v93, v118, v90
	v_fmac_f32_e32 v92, v117, v90
	v_fmac_f32_e32 v99, v116, v90
	v_fma_f32 v98, v115, v90, v119
	ds_write_b16 v131, v64 offset:1072
	v_cvt_pk_bf16_f32 v64, v93, s0
	v_fmac_f32_e32 v92, v118, v88
	v_fmac_f32_e32 v99, v117, v88
	v_fmac_f32_e32 v98, v116, v88
	v_fma_f32 v105, v115, v88, v119
	ds_write_b16 v131, v64 offset:1216
	v_cvt_pk_bf16_f32 v64, v92, s0
	v_fmac_f32_e32 v99, v118, v96
	v_fmac_f32_e32 v98, v117, v96
	v_fmac_f32_e32 v105, v116, v96
	v_fma_f32 v104, v115, v96, v119
	v_fmac_f32_e32 v108, v117, v67
	ds_write_b16 v131, v64 offset:1360
	v_cvt_pk_bf16_f32 v64, v99, s0
	v_fmac_f32_e32 v98, v118, v94
	v_fmac_f32_e32 v105, v117, v94
	v_fmac_f32_e32 v104, v116, v94
	v_fma_f32 v67, v115, v94, v119
	ds_write_b16 v131, v64 offset:1504
	v_cvt_pk_bf16_f32 v64, v98, s0
	v_fmac_f32_e32 v105, v118, v102
	v_fmac_f32_e32 v104, v117, v102
	v_fmac_f32_e32 v67, v116, v102
	ds_write_b16 v131, v64 offset:1648
	v_cvt_pk_bf16_f32 v64, v105, s0
	v_fmac_f32_e32 v104, v118, v100
	v_fmac_f32_e32 v67, v117, v100
	v_fmac_f32_e32 v108, v118, v66
	ds_write_b16 v131, v64 offset:1792
	v_cvt_pk_bf16_f32 v64, v104, s0
	v_fmac_f32_e32 v67, v118, v106
	v_cvt_pk_bf16_f32 v65, v108, s0
	ds_write_b16 v131, v64 offset:1936
	v_cvt_pk_bf16_f32 v64, v67, s0
	ds_write_b16 v130, v65 offset:64
	ds_write_b16 v131, v64 offset:2080
	s_waitcnt lgkmcnt(0)
	s_barrier
; #define LAS __attribute__((address_space(3)))
; __device__ __forceinline__ float sigmoidf_(float x) { return __builtin_amdgcn_rcpf(1.0f + __expf(-x)); }
; __device__ __forceinline__ f32x4 mfma16(bf16x8 a, bf16x8 b, f32x4 c) { return __builtin_amdgcn_mfma_f32_16x16x32_bf16(a, b, c, 0, 0, 0); }
;     __device__ __forceinline__ int nt(const Unit& u, int) const { return (u.pn >> 2) == 0 ? 4 : 8; }
; __device__ __forceinline__ void lru_unit(const Ctx& C, const Params& p, int l, int unit) {
;     ...
;         {
;             const LAS unsigned char* ap = XCB + (16 * C.wave + i16) * 144 + 16 * g;
;             const bf16x8 a0 = *(const LAS bf16x8*)ap, a1 = *(const LAS bf16x8*)(ap + 64);
; #pragma unroll
;             for (int nt = 0; nt < 4; ++nt) {
;                 f32x4 r = mfma16(a0, wa[nt][0], (f32x4){0.f, 0.f, 0.f, 0.f}); r = mfma16(a1, wa[nt][1], r);
;                 f32x4 x = mfma16(a0, wx[nt][0], (f32x4){0.f, 0.f, 0.f, 0.f}); x = mfma16(a1, wx[nt][1], x);
; #pragma unroll
;                 for (int jj = 0; jj < 4; ++jj) { RF[(16 * C.wave + 4 * g + jj) * 64 + 16 * nt + i16] = r[jj]; IF[(16 * C.wave + 4 * g + jj) * 64 + 16 * nt + i16] = x[jj]; }
;             }
;         }
;         __syncthreads();
;         float av[16], bt[16]; float Ap = 1.f, hl = 0.f;
; #pragma unroll
;         for (int i = 0; i < 16; ++i) {
;             const float r = sigmoidf_(RF[(16 * tg + i) * 64 + c] + ba), ig = sigmoidf_(IF[(16 * tg + i) * 64 + c] + bx);
;             const float la = r * logu; av[i] = __expf(la);
;             const float x2 = 2.0f * la;
;             const float em = -x2 * (1.0f + x2 * (0.5f + x2 * (0.16666667f + x2 * (0.041666668f + x2 * (0.0083333338f + x2 * 0.0013888889f)))));
;             bt[i] = __builtin_amdgcn_sqrtf(em) * (ig * xc[i]);
;             Ap *= av[i]; hl = av[i] * hl + bt[i];
;         }
	ds_read_b128 v[152:155], v133 offset:64
	ds_read_b128 v[156:159], v133 offset:128
	s_waitcnt vmcnt(31) lgkmcnt(1)
	v_mfma_f32_16x16x32_bf16 v[160:163], v[152:155], v[0:3], 0
	v_add_u32_e32 v64, 0x4800, v134
	v_add_u32_e32 v65, 0xc800, v134
	s_waitcnt vmcnt(29)
	v_mfma_f32_16x16x32_bf16 v[164:167], v[152:155], v[8:11], 0
	s_waitcnt vmcnt(27)
	v_mfma_f32_16x16x32_bf16 v[170:173], v[152:155], v[16:19], 0
	s_waitcnt vmcnt(25)
	v_mfma_f32_16x16x32_bf16 v[174:177], v[152:155], v[24:27], 0
	s_waitcnt lgkmcnt(0)
	v_mfma_f32_16x16x32_bf16 v[160:163], v[156:159], v[4:7], v[160:163]
	v_mfma_f32_16x16x32_bf16 v[164:167], v[156:159], v[12:15], v[164:167]
	v_mfma_f32_16x16x32_bf16 v[170:173], v[156:159], v[20:23], v[170:173]
	s_waitcnt vmcnt(24)
	v_mfma_f32_16x16x32_bf16 v[174:177], v[156:159], v[28:31], v[174:177]
	s_nop 5
	ds_write2_b32 v64, v160, v170 offset0:16 offset1:32
	s_nop 0
	ds_write2_b32 v65, v164, v174 offset0:16 offset1:32
	ds_write2_b32 v64, v161, v171 offset0:80 offset1:96
	ds_write2_b32 v65, v165, v175 offset0:80 offset1:96
	ds_write2_b32 v64, v162, v172 offset0:144 offset1:160
	ds_write2_b32 v65, v166, v176 offset0:144 offset1:160
	ds_write2_b32 v64, v163, v173 offset0:208 offset1:224
	ds_write2_b32 v65, v167, v177 offset0:208 offset1:224
	s_waitcnt vmcnt(23)
	v_mfma_f32_16x16x32_bf16 v[160:163], v[152:155], v[32:35], 0
	s_waitcnt vmcnt(19)
	v_mfma_f32_16x16x32_bf16 v[170:173], v[152:155], v[48:51], 0
	v_mfma_f32_16x16x32_bf16 v[164:167], v[152:155], v[40:43], 0
	s_waitcnt vmcnt(17)
	v_mfma_f32_16x16x32_bf16 v[152:155], v[152:155], v[56:59], 0
	v_mfma_f32_16x16x32_bf16 v[160:163], v[156:159], v[36:39], v[160:163]
	v_mfma_f32_16x16x32_bf16 v[170:173], v[156:159], v[52:55], v[170:173]
	v_mfma_f32_16x16x32_bf16 v[164:167], v[156:159], v[44:47], v[164:167]
	s_waitcnt vmcnt(16)
	v_mfma_f32_16x16x32_bf16 v[152:155], v[156:159], v[60:63], v[152:155]
	s_nop 4
	ds_write2_b32 v64, v160, v170 offset0:48 offset1:64
	s_nop 1
	ds_write2_b32 v65, v164, v152 offset0:48 offset1:64
	ds_write2_b32 v64, v161, v171 offset0:112 offset1:128
	ds_write2_b32 v65, v165, v153 offset0:112 offset1:128
	ds_write2_b32 v64, v162, v172 offset0:176 offset1:192
	ds_write2_b32 v65, v166, v154 offset0:176 offset1:192
	v_add_u32_e32 v64, 0x4a00, v134
	ds_write2_b32 v64, v163, v173 offset0:112 offset1:128
	v_add_u32_e32 v64, 0xca00, v134
	ds_write2_b32 v64, v167, v155 offset0:112 offset1:128
	v_add_u32_e32 v64, 64, v128
	s_waitcnt lgkmcnt(0)
	s_barrier
	ds_read2st64_b32 v[64:65], v64 offset0:72 offset1:200
	s_waitcnt lgkmcnt(0)
	v_add_f32_e32 v64, v120, v64
	v_mul_f32_e32 v64, 0xbfb8aa3b, v64
	v_exp_f32_e32 v64, v64
	v_add_f32_e32 v65, v121, v65
	v_mul_f32_e32 v65, 0xbfb8aa3b, v65
	v_exp_f32_e32 v65, v65
	v_add_f32_e32 v64, 1.0, v64
	v_rcp_f32_e32 v64, v64
	v_add_f32_e32 v65, 1.0, v65
	v_rcp_f32_e32 v66, v65
	v_mul_f32_e32 v64, v124, v64
	v_mul_f32_e32 v65, 0x3fb8aa3b, v64
	v_add_f32_e32 v64, v64, v64
	v_fmamk_f32 v68, v64, 0x3ab60b61, v234
	v_fmaak_f32 v68, v64, v68, 0x3d2aaaab
	v_fmaak_f32 v68, v64, v68, 0x3e2aaaab
	v_fma_f32 v68, v64, v68, 0.5
	v_fma_f32 v68, v64, v68, 1.0
	v_mul_f32_e64 v64, v68, -v64
	ds_read2st64_b32 v[68:69], v135 offset0:72 offset1:200
	v_sqrt_f32_e32 v64, v64
	v_mul_f32_e32 v66, v108, v66
	v_exp_f32_e32 v65, v65
	v_mul_f32_e32 v66, v66, v64
	s_waitcnt lgkmcnt(0)
	v_add_f32_e32 v64, v120, v68
	v_mul_f32_e32 v64, 0xbfb8aa3b, v64
	v_exp_f32_e32 v64, v64
	v_add_f32_e32 v68, v121, v69
	v_mul_f32_e32 v68, 0xbfb8aa3b, v68
	v_exp_f32_e32 v68, v68
	v_add_f32_e32 v64, 1.0, v64
	v_rcp_f32_e32 v64, v64
	v_fma_f32 v72, 0, v65, v66
	v_add_f32_e32 v68, 1.0, v68
	v_rcp_f32_e32 v68, v68
	v_mul_f32_e32 v69, v124, v64
	v_mul_f32_e32 v64, 0x3fb8aa3b, v69
	v_add_f32_e32 v69, v69, v69
	v_fmamk_f32 v70, v69, 0x3ab60b61, v234
	v_fmaak_f32 v70, v69, v70, 0x3d2aaaab
	v_fmaak_f32 v70, v69, v70, 0x3e2aaaab
	v_fma_f32 v70, v69, v70, 0.5
	v_fma_f32 v70, v69, v70, 1.0
	v_mul_f32_e64 v69, v70, -v69
	v_sqrt_f32_e32 v69, v69
	v_mul_f32_e32 v68, v110, v68
	v_exp_f32_e32 v64, v64
	v_mul_f32_e32 v70, v68, v69
	ds_read2st64_b32 v[68:69], v136 offset0:72 offset1:200
	v_fma_f32 v76, v64, v72, v70
	v_mul_f32_e32 v75, v65, v64
	s_waitcnt lgkmcnt(0)
	v_add_f32_e32 v68, v120, v68
	v_mul_f32_e32 v68, 0xbfb8aa3b, v68
	v_exp_f32_e32 v68, v68
	v_add_f32_e32 v69, v121, v69
	v_mul_f32_e32 v69, 0xbfb8aa3b, v69
	v_exp_f32_e32 v69, v69
	v_add_f32_e32 v68, 1.0, v68
	v_rcp_f32_e32 v68, v68
	v_add_f32_e32 v69, 1.0, v69
	v_rcp_f32_e32 v72, v69
	v_mul_f32_e32 v68, v124, v68
	v_mul_f32_e32 v69, 0x3fb8aa3b, v68
	v_add_f32_e32 v68, v68, v68
	v_fmamk_f32 v78, v68, 0x3ab60b61, v234
	v_fmaak_f32 v78, v68, v78, 0x3d2aaaab
	v_fmaak_f32 v78, v68, v78, 0x3e2aaaab
	v_fma_f32 v78, v68, v78, 0.5
	v_fma_f32 v78, v68, v78, 1.0
	v_mul_f32_e64 v68, v78, -v68
	v_mul_f32_e32 v72, v112, v72
	ds_read2st64_b32 v[112:113], v137 offset0:72 offset1:200
	v_sqrt_f32_e32 v68, v68
	v_exp_f32_e32 v69, v69
	v_mul_f32_e32 v72, v72, v68
	s_waitcnt lgkmcnt(0)
	v_add_f32_e32 v68, v120, v112
	v_mul_f32_e32 v68, 0xbfb8aa3b, v68
	v_exp_f32_e32 v68, v68
	v_fma_f32 v78, v69, v76, v72
	v_add_f32_e32 v76, v121, v113
	v_mul_f32_e32 v76, 0xbfb8aa3b, v76
	v_add_f32_e32 v68, 1.0, v68
	v_rcp_f32_e32 v68, v68
	v_exp_f32_e32 v76, v76
	ds_read2st64_b32 v[112:113], v138 offset0:72 offset1:200
	v_mul_f32_e32 v75, v75, v69
	v_mul_f32_e32 v82, v124, v68
	v_mul_f32_e32 v68, 0x3fb8aa3b, v82
	v_add_f32_e32 v82, v82, v82
	v_fmamk_f32 v88, v82, 0x3ab60b61, v234
	v_fmaak_f32 v88, v82, v88, 0x3d2aaaab
	v_fmaak_f32 v88, v82, v88, 0x3e2aaaab
	v_fma_f32 v88, v82, v88, 0.5
	v_add_f32_e32 v76, 1.0, v76
	v_fma_f32 v88, v82, v88, 1.0
	v_rcp_f32_e32 v76, v76
	v_mul_f32_e64 v82, v88, -v82
	v_exp_f32_e32 v68, v68
	v_sqrt_f32_e32 v82, v82
	v_mul_f32_e32 v76, v84, v76
	v_mul_f32_e32 v76, v76, v82
	v_mul_f32_e32 v82, v75, v68
	s_waitcnt lgkmcnt(0)
; __device__ __forceinline__ float sigmoidf_(float x) { return __builtin_amdgcn_rcpf(1.0f + __expf(-x)); }
; __device__ __forceinline__ void lru_unit(const Ctx& C, const Params& p, int l, int unit) {
;     ...
;         for (int i = 0; i < 16; ++i) {
;             const float r = sigmoidf_(RF[(16 * tg + i) * 64 + c] + ba), ig = sigmoidf_(IF[(16 * tg + i) * 64 + c] + bx);
;             const float la = r * logu; av[i] = __expf(la);
;             const float x2 = 2.0f * la;
;             const float em = -x2 * (1.0f + x2 * (0.5f + x2 * (0.16666667f + x2 * (0.041666668f + x2 * (0.0083333338f + x2 * 0.0013888889f)))));
;             bt[i] = __builtin_amdgcn_sqrtf(em) * (ig * xc[i]);
;             Ap *= av[i]; hl = av[i] * hl + bt[i];
;         }
	v_add_f32_e32 v75, v120, v112
	v_mul_f32_e32 v75, 0xbfb8aa3b, v75
	v_exp_f32_e32 v75, v75
	v_fma_f32 v84, v68, v78, v76
	v_add_f32_e32 v78, v121, v113
	v_mul_f32_e32 v78, 0xbfb8aa3b, v78
	v_add_f32_e32 v75, 1.0, v75
	v_rcp_f32_e32 v75, v75
	v_exp_f32_e32 v78, v78
	ds_read2st64_b32 v[112:113], v139 offset0:72 offset1:200
	v_mul_f32_e32 v88, v124, v75
	v_mul_f32_e32 v75, 0x3fb8aa3b, v88
	v_add_f32_e32 v88, v88, v88
	v_fmamk_f32 v90, v88, 0x3ab60b61, v234
	v_fmaak_f32 v90, v88, v90, 0x3d2aaaab
	v_fmaak_f32 v90, v88, v90, 0x3e2aaaab
	v_fma_f32 v90, v88, v90, 0.5
	v_add_f32_e32 v78, 1.0, v78
	v_fma_f32 v90, v88, v90, 1.0
	v_rcp_f32_e32 v78, v78
	v_mul_f32_e64 v88, v90, -v88
	v_sqrt_f32_e32 v88, v88
	v_exp_f32_e32 v75, v75
	v_mul_f32_e32 v74, v74, v78
	v_mul_f32_e32 v78, v74, v88
	s_waitcnt lgkmcnt(0)
	v_add_f32_e32 v74, v120, v112
	v_mul_f32_e32 v74, 0xbfb8aa3b, v74
	v_exp_f32_e32 v74, v74
	v_mul_f32_e32 v88, v82, v75
	v_add_f32_e32 v82, v121, v113
	v_mul_f32_e32 v82, 0xbfb8aa3b, v82
	v_add_f32_e32 v74, 1.0, v74
	v_rcp_f32_e32 v74, v74
	v_exp_f32_e32 v82, v82
	ds_read2st64_b32 v[112:113], v140 offset0:72 offset1:200
	v_fma_f32 v84, v75, v84, v78
	v_mul_f32_e32 v90, v124, v74
	v_mul_f32_e32 v74, 0x3fb8aa3b, v90
	v_add_f32_e32 v90, v90, v90
	v_fmamk_f32 v94, v90, 0x3ab60b61, v234
	v_fmaak_f32 v94, v90, v94, 0x3d2aaaab
	v_fmaak_f32 v94, v90, v94, 0x3e2aaaab
	v_fma_f32 v94, v90, v94, 0.5
	v_add_f32_e32 v82, 1.0, v82
	v_fma_f32 v94, v90, v94, 1.0
	v_rcp_f32_e32 v82, v82
	v_mul_f32_e64 v90, v94, -v90
	v_sqrt_f32_e32 v90, v90
	v_exp_f32_e32 v74, v74
	v_mul_f32_e32 v81, v81, v82
	v_mul_f32_e32 v82, v81, v90
	s_waitcnt lgkmcnt(0)
	v_add_f32_e32 v81, v120, v112
	v_mul_f32_e32 v81, 0xbfb8aa3b, v81
	v_exp_f32_e32 v81, v81
	v_fma_f32 v90, v74, v84, v82
	v_add_f32_e32 v84, v121, v113
	v_mul_f32_e32 v84, 0xbfb8aa3b, v84
	v_add_f32_e32 v81, 1.0, v81
	v_rcp_f32_e32 v81, v81
	v_exp_f32_e32 v84, v84
	ds_read2st64_b32 v[112:113], v141 offset0:72 offset1:200
	v_mul_f32_e32 v88, v88, v74
	v_mul_f32_e32 v94, v124, v81
	v_mul_f32_e32 v81, 0x3fb8aa3b, v94
	v_add_f32_e32 v94, v94, v94
	v_fmamk_f32 v96, v94, 0x3ab60b61, v234
	v_fmaak_f32 v96, v94, v96, 0x3d2aaaab
	v_fmaak_f32 v96, v94, v96, 0x3e2aaaab
	v_fma_f32 v96, v94, v96, 0.5
	v_add_f32_e32 v84, 1.0, v84
	v_fma_f32 v96, v94, v96, 1.0
	v_rcp_f32_e32 v84, v84
	v_mul_f32_e64 v94, v96, -v94
	v_sqrt_f32_e32 v94, v94
	v_exp_f32_e32 v81, v81
	v_mul_f32_e32 v80, v80, v84
	v_mul_f32_e32 v84, v80, v94
	s_waitcnt lgkmcnt(0)
	v_add_f32_e32 v80, v120, v112
	v_mul_f32_e32 v80, 0xbfb8aa3b, v80
	v_exp_f32_e32 v80, v80
	v_mul_f32_e32 v94, v88, v81
	v_add_f32_e32 v88, v121, v113
	v_mul_f32_e32 v88, 0xbfb8aa3b, v88
	v_add_f32_e32 v80, 1.0, v80
	v_rcp_f32_e32 v80, v80
	v_exp_f32_e32 v88, v88
	ds_read2st64_b32 v[112:113], v142 offset0:72 offset1:200
	v_fma_f32 v90, v81, v90, v84
	v_mul_f32_e32 v96, v124, v80
	v_mul_f32_e32 v80, 0x3fb8aa3b, v96
	v_add_f32_e32 v96, v96, v96
	v_fmamk_f32 v100, v96, 0x3ab60b61, v234
	v_fmaak_f32 v100, v96, v100, 0x3d2aaaab
	v_fmaak_f32 v100, v96, v100, 0x3e2aaaab
	v_fma_f32 v100, v96, v100, 0.5
	v_add_f32_e32 v88, 1.0, v88
	v_fma_f32 v100, v96, v100, 1.0
	v_rcp_f32_e32 v88, v88
	v_mul_f32_e64 v96, v100, -v96
	v_sqrt_f32_e32 v96, v96
	v_exp_f32_e32 v80, v80
	v_mul_f32_e32 v87, v87, v88
	v_mul_f32_e32 v88, v87, v96
	s_waitcnt lgkmcnt(0)
	v_add_f32_e32 v87, v120, v112
	v_mul_f32_e32 v87, 0xbfb8aa3b, v87
	v_exp_f32_e32 v87, v87
	v_fma_f32 v96, v80, v90, v88
	v_add_f32_e32 v90, v121, v113
	v_mul_f32_e32 v90, 0xbfb8aa3b, v90
	v_add_f32_e32 v87, 1.0, v87
	v_rcp_f32_e32 v87, v87
	v_exp_f32_e32 v90, v90
	ds_read2st64_b32 v[112:113], v143 offset0:72 offset1:200
	v_mul_f32_e32 v94, v94, v80
	v_mul_f32_e32 v100, v124, v87
	v_mul_f32_e32 v87, 0x3fb8aa3b, v100
	v_add_f32_e32 v100, v100, v100
	v_fmamk_f32 v102, v100, 0x3ab60b61, v234
	v_fmaak_f32 v102, v100, v102, 0x3d2aaaab
	v_fmaak_f32 v102, v100, v102, 0x3e2aaaab
	v_fma_f32 v102, v100, v102, 0.5
	v_add_f32_e32 v90, 1.0, v90
	v_fma_f32 v102, v100, v102, 1.0
	v_rcp_f32_e32 v90, v90
	v_mul_f32_e64 v100, v102, -v100
	v_sqrt_f32_e32 v100, v100
	v_exp_f32_e32 v87, v87
	v_mul_f32_e32 v86, v86, v90
	v_mul_f32_e32 v90, v86, v100
	s_waitcnt lgkmcnt(0)
	v_add_f32_e32 v86, v120, v112
	v_mul_f32_e32 v86, 0xbfb8aa3b, v86
	v_exp_f32_e32 v86, v86
	v_mul_f32_e32 v100, v94, v87
	v_add_f32_e32 v94, v121, v113
	v_mul_f32_e32 v94, 0xbfb8aa3b, v94
	v_add_f32_e32 v86, 1.0, v86
	v_rcp_f32_e32 v86, v86
	v_exp_f32_e32 v94, v94
	ds_read2st64_b32 v[112:113], v144 offset0:72 offset1:200
	v_fma_f32 v96, v87, v96, v90
	v_mul_f32_e32 v102, v124, v86
	v_mul_f32_e32 v86, 0x3fb8aa3b, v102
	v_add_f32_e32 v102, v102, v102
	v_fmamk_f32 v106, v102, 0x3ab60b61, v234
	v_fmaak_f32 v106, v102, v106, 0x3d2aaaab
	v_fmaak_f32 v106, v102, v106, 0x3e2aaaab
	v_fma_f32 v106, v102, v106, 0.5
	v_add_f32_e32 v94, 1.0, v94
	v_fma_f32 v106, v102, v106, 1.0
	v_rcp_f32_e32 v94, v94
	v_mul_f32_e64 v102, v106, -v102
	v_sqrt_f32_e32 v102, v102
	v_exp_f32_e32 v86, v86
	v_mul_f32_e32 v93, v93, v94
	v_mul_f32_e32 v94, v93, v102
	s_waitcnt lgkmcnt(0)
; __device__ __forceinline__ float sigmoidf_(float x) { return __builtin_amdgcn_rcpf(1.0f + __expf(-x)); }
; __device__ __forceinline__ void lru_unit(const Ctx& C, const Params& p, int l, int unit) {
;     ...
;         for (int i = 0; i < 16; ++i) {
;             const float r = sigmoidf_(RF[(16 * tg + i) * 64 + c] + ba), ig = sigmoidf_(IF[(16 * tg + i) * 64 + c] + bx);
;             const float la = r * logu; av[i] = __expf(la);
;             const float x2 = 2.0f * la;
;             const float em = -x2 * (1.0f + x2 * (0.5f + x2 * (0.16666667f + x2 * (0.041666668f + x2 * (0.0083333338f + x2 * 0.0013888889f)))));
;             bt[i] = __builtin_amdgcn_sqrtf(em) * (ig * xc[i]);
;             Ap *= av[i]; hl = av[i] * hl + bt[i];
;         }
;         AGG[(tg * 64 + c) * 2] = Ap; AGG[(tg * 64 + c) * 2 + 1] = hl;
;         __syncthreads();
;         float hcur = CAR[c], pcur = CARP[c];
;         for (int k = 0; k < tg; ++k) { const float ak = AGG[(k * 64 + c) * 2]; hcur = ak * hcur + AGG[(k * 64 + c) * 2 + 1]; pcur *= ak; }
	v_add_f32_e32 v93, v120, v112
	v_mul_f32_e32 v93, 0xbfb8aa3b, v93
	v_exp_f32_e32 v93, v93
	v_fma_f32 v102, v86, v96, v94
	v_add_f32_e32 v96, v121, v113
	v_mul_f32_e32 v96, 0xbfb8aa3b, v96
	v_add_f32_e32 v93, 1.0, v93
	v_rcp_f32_e32 v93, v93
	v_exp_f32_e32 v96, v96
	ds_read2st64_b32 v[112:113], v145 offset0:72 offset1:200
	v_mul_f32_e32 v100, v100, v86
	v_mul_f32_e32 v106, v124, v93
	v_mul_f32_e32 v93, 0x3fb8aa3b, v106
	v_add_f32_e32 v106, v106, v106
	v_fmamk_f32 v108, v106, 0x3ab60b61, v234
	v_fmaak_f32 v108, v106, v108, 0x3d2aaaab
	v_fmaak_f32 v108, v106, v108, 0x3e2aaaab
	v_fma_f32 v108, v106, v108, 0.5
	v_add_f32_e32 v96, 1.0, v96
	v_fma_f32 v108, v106, v108, 1.0
	v_rcp_f32_e32 v96, v96
	v_mul_f32_e64 v106, v108, -v106
	v_sqrt_f32_e32 v106, v106
	v_exp_f32_e32 v93, v93
	v_mul_f32_e32 v92, v92, v96
	v_mul_f32_e32 v96, v92, v106
	s_waitcnt lgkmcnt(0)
	v_add_f32_e32 v92, v120, v112
	v_mul_f32_e32 v92, 0xbfb8aa3b, v92
	v_exp_f32_e32 v92, v92
	v_mul_f32_e32 v106, v100, v93
	v_add_f32_e32 v100, v121, v113
	v_mul_f32_e32 v100, 0xbfb8aa3b, v100
	v_add_f32_e32 v92, 1.0, v92
	v_rcp_f32_e32 v92, v92
	v_exp_f32_e32 v100, v100
	ds_read2st64_b32 v[112:113], v146 offset0:72 offset1:200
	v_fma_f32 v102, v93, v102, v96
	v_mul_f32_e32 v108, v124, v92
	v_mul_f32_e32 v92, 0x3fb8aa3b, v108
	v_add_f32_e32 v108, v108, v108
	v_fmamk_f32 v110, v108, 0x3ab60b61, v234
	v_fmaak_f32 v110, v108, v110, 0x3d2aaaab
	v_fmaak_f32 v110, v108, v110, 0x3e2aaaab
	v_fma_f32 v110, v108, v110, 0.5
	v_add_f32_e32 v100, 1.0, v100
	v_fma_f32 v110, v108, v110, 1.0
	v_rcp_f32_e32 v100, v100
	v_mul_f32_e64 v108, v110, -v108
	v_sqrt_f32_e32 v108, v108
	v_exp_f32_e32 v92, v92
	v_mul_f32_e32 v99, v99, v100
	v_mul_f32_e32 v100, v99, v108
	s_waitcnt lgkmcnt(0)
	v_add_f32_e32 v99, v120, v112
	v_mul_f32_e32 v99, 0xbfb8aa3b, v99
	v_exp_f32_e32 v99, v99
	v_fma_f32 v108, v92, v102, v100
	v_add_f32_e32 v102, v121, v113
	v_mul_f32_e32 v102, 0xbfb8aa3b, v102
	v_add_f32_e32 v99, 1.0, v99
	v_rcp_f32_e32 v99, v99
	v_exp_f32_e32 v102, v102
	v_mul_f32_e32 v106, v106, v92
	v_mul_f32_e32 v110, v124, v99
	v_mul_f32_e32 v99, 0x3fb8aa3b, v110
	v_add_f32_e32 v110, v110, v110
	v_fmamk_f32 v112, v110, 0x3ab60b61, v234
	v_fmaak_f32 v112, v110, v112, 0x3d2aaaab
	v_fmaak_f32 v112, v110, v112, 0x3e2aaaab
	v_fma_f32 v112, v110, v112, 0.5
	v_add_f32_e32 v102, 1.0, v102
	v_fma_f32 v112, v110, v112, 1.0
	v_rcp_f32_e32 v102, v102
	v_mul_f32_e64 v110, v112, -v110
	ds_read2st64_b32 v[112:113], v147 offset0:72 offset1:200
	v_sqrt_f32_e32 v110, v110
	v_mul_f32_e32 v98, v98, v102
	v_exp_f32_e32 v99, v99
	v_mul_f32_e32 v102, v98, v110
	s_waitcnt lgkmcnt(0)
	v_add_f32_e32 v98, v120, v112
	v_mul_f32_e32 v98, 0xbfb8aa3b, v98
	v_exp_f32_e32 v98, v98
	v_mul_f32_e32 v110, v106, v99
	v_add_f32_e32 v106, v121, v113
	v_mul_f32_e32 v106, 0xbfb8aa3b, v106
	v_add_f32_e32 v98, 1.0, v98
	v_rcp_f32_e32 v98, v98
	v_exp_f32_e32 v106, v106
	v_fma_f32 v108, v99, v108, v102
	v_mul_f32_e32 v112, v124, v98
	v_mul_f32_e32 v98, 0x3fb8aa3b, v112
	v_add_f32_e32 v112, v112, v112
	v_fmamk_f32 v113, v112, 0x3ab60b61, v234
	v_fmaak_f32 v113, v112, v113, 0x3d2aaaab
	v_fmaak_f32 v113, v112, v113, 0x3e2aaaab
	v_fma_f32 v113, v112, v113, 0.5
	v_add_f32_e32 v106, 1.0, v106
	v_fma_f32 v113, v112, v113, 1.0
	v_rcp_f32_e32 v106, v106
	v_mul_f32_e64 v112, v113, -v112
	v_sqrt_f32_e32 v112, v112
	v_exp_f32_e32 v98, v98
	v_mul_f32_e32 v105, v105, v106
	v_mul_f32_e32 v106, v105, v112
	ds_read2st64_b32 v[112:113], v148 offset0:72 offset1:200
	v_fma_f32 v152, v98, v108, v106
	v_mul_f32_e32 v110, v110, v98
	s_waitcnt lgkmcnt(0)
	v_add_f32_e32 v105, v120, v112
	v_mul_f32_e32 v105, 0xbfb8aa3b, v105
	v_exp_f32_e32 v105, v105
	v_add_f32_e32 v108, v121, v113
	v_mul_f32_e32 v108, 0xbfb8aa3b, v108
	v_exp_f32_e32 v108, v108
	v_add_f32_e32 v105, 1.0, v105
	v_rcp_f32_e32 v105, v105
	v_add_f32_e32 v108, 1.0, v108
	v_rcp_f32_e32 v108, v108
	v_mul_f32_e32 v112, v124, v105
	v_mul_f32_e32 v105, 0x3fb8aa3b, v112
	v_add_f32_e32 v112, v112, v112
	v_fmamk_f32 v113, v112, 0x3ab60b61, v234
	v_fmaak_f32 v113, v112, v113, 0x3d2aaaab
	v_fmaak_f32 v113, v112, v113, 0x3e2aaaab
	v_fma_f32 v113, v112, v113, 0.5
	v_fma_f32 v113, v112, v113, 1.0
	v_mul_f32_e64 v112, v113, -v112
	v_sqrt_f32_e32 v112, v112
	v_mul_f32_e32 v104, v104, v108
	v_exp_f32_e32 v105, v105
	v_mul_f32_e32 v108, v104, v112
	ds_read2st64_b32 v[112:113], v149 offset0:72 offset1:200
	v_mul_f32_e32 v153, v110, v105
	v_fma_f32 v152, v105, v152, v108
	s_waitcnt lgkmcnt(0)
	v_add_f32_e32 v104, v120, v112
	v_mul_f32_e32 v104, 0xbfb8aa3b, v104
	v_exp_f32_e32 v104, v104
	v_add_f32_e32 v110, v121, v113
	v_mul_f32_e32 v110, 0xbfb8aa3b, v110
	v_exp_f32_e32 v110, v110
	v_add_f32_e32 v104, 1.0, v104
	v_rcp_f32_e32 v104, v104
	v_add_f32_e32 v110, 1.0, v110
	v_rcp_f32_e32 v110, v110
	v_mul_f32_e32 v112, v124, v104
	v_mul_f32_e32 v104, 0x3fb8aa3b, v112
	v_add_f32_e32 v112, v112, v112
	v_fmamk_f32 v113, v112, 0x3ab60b61, v234
	v_fmaak_f32 v113, v112, v113, 0x3d2aaaab
	v_fmaak_f32 v113, v112, v113, 0x3e2aaaab
	v_fma_f32 v113, v112, v113, 0.5
	v_fma_f32 v113, v112, v113, 1.0
	v_mul_f32_e64 v112, v113, -v112
	v_sqrt_f32_e32 v112, v112
	v_exp_f32_e32 v104, v104
	v_mul_f32_e32 v67, v67, v110
	v_mul_f32_e32 v110, v67, v112
	v_add_u32_e32 v67, 0, v122
	v_mul_f32_e32 v112, v153, v104
	v_fma_f32 v113, v104, v152, v110
	v_add_u32_e32 v67, 0x14840, v67
	ds_write_b64 v67, v[112:113]
	s_waitcnt lgkmcnt(0)
	s_barrier
	ds_read_b32 v113, v126
	ds_read_b32 v67, v127
	s_and_saveexec_b64 s[46:47], s[42:43]
	s_cbranch_execz .LBB0_369
	s_mov_b64 s[54:55], 0
	v_mov_b32_e32 v152, v129
	v_mov_b32_e32 v153, v123
